# down-proj epilogue rewritten by hand: all 32 residual loads up front with counted vmcnt waits (second half's loads no longer queue behind the first half's stores), scalar-base addressing
# speedup vs baseline: 1.0372x; 1.0372x over previous
;     DI void operator()(const AccT& acc, const Unit& u, int wr, int wc, int fr, int fq, LAS unsigned char*) const {
;         const int col0 = u.pn * 256 + wc * 32 + 4 * fq;
; #pragma unroll
;         for (int ai = 0; ai < 2; ++ai) {
;             u32x2 xb[4][2][2];
; #pragma unroll
;             for (int m = 0; m < 4; ++m) {
;                 const int row = u.pm * 256 + ai * 128 + wr * 64 + m * 16 + fr;
;                 const bf16_t* brow = X1B + (size_t)(row < SEQ ? row + 2 : row + (X1B_PROMPT_ROWS - SEQ)) * DM + col0;
; #pragma unroll
;                 for (int bj = 0; bj < 2; ++bj)
; #pragma unroll
;                     for (int n = 0; n < 2; ++n) xb[m][bj][n] = *(const u32x2*)(brow + bj * 128 + n * 16);
;             }
;             asm volatile("" ::: "memory");
; #pragma unroll
;             for (int m = 0; m < 4; ++m) {
;                 const int row = u.pm * 256 + ai * 128 + wr * 64 + m * 16 + fr;
;                 float* orow = out + (size_t)row * DM + col0;
; #pragma unroll
;                 for (int bj = 0; bj < 2; ++bj)
; #pragma unroll
;                     for (int n = 0; n < 2; ++n) { const u32x2 b = xb[m][bj][n];
;                         const f32x4 xr = {__uint_as_float(b.x << 16), __uint_as_float(b.x & 0xffff0000u), __uint_as_float(b.y << 16), __uint_as_float(b.y & 0xffff0000u)};
;                         *(f32x4*)(orow + bj * 128 + n * 16) = xr + acc[ai][bj][m][n]; }
.LBB0_794:
	v_lshl_add_u32 v132, s21, 8, v164
	v_lshl_or_b32 v128, s30, 8, v166
	s_cmp_lt_i32 s21, 64
	s_cselect_b32 s43, 1, 64
	s_lshl_b32 s43, s43, 12
	s_add_u32 s16, s56, s43
	s_addc_u32 s17, s57, 0
	v_lshlrev_b32_e32 v129, 11, v132
	v_lshlrev_b32_e32 v133, 12, v132
	v_lshl_add_u32 v129, v128, 1, v129
	v_lshl_add_u32 v133, v128, 2, v133
	global_load_dwordx2 v[136:137], v129, s[16:17]
	global_load_dwordx2 v[138:139], v129, s[16:17] offset:32
	global_load_dwordx2 v[140:141], v129, s[16:17] offset:256
	global_load_dwordx2 v[142:143], v129, s[16:17] offset:288
	s_add_u32 s18, s16, 0x8000
	s_addc_u32 s19, s17, 0
	global_load_dwordx2 v[144:145], v129, s[18:19]
	global_load_dwordx2 v[146:147], v129, s[18:19] offset:32
	global_load_dwordx2 v[148:149], v129, s[18:19] offset:256
	global_load_dwordx2 v[150:151], v129, s[18:19] offset:288
	s_add_u32 s18, s16, 0x10000
	s_addc_u32 s19, s17, 0
	global_load_dwordx2 v[152:153], v129, s[18:19]
	global_load_dwordx2 v[154:155], v129, s[18:19] offset:32
	global_load_dwordx2 v[156:157], v129, s[18:19] offset:256
	global_load_dwordx2 v[158:159], v129, s[18:19] offset:288
	s_add_u32 s18, s16, 0x18000
	s_addc_u32 s19, s17, 0
	global_load_dwordx2 v[160:161], v129, s[18:19]
	global_load_dwordx2 v[162:163], v129, s[18:19] offset:32
	global_load_dwordx2 v[182:183], v129, s[18:19] offset:256
	global_load_dwordx2 v[184:185], v129, s[18:19] offset:288
	s_add_u32 s18, s16, 0x40000
	s_addc_u32 s19, s17, 0
	global_load_dwordx2 v[186:187], v129, s[18:19]
	global_load_dwordx2 v[188:189], v129, s[18:19] offset:32
	global_load_dwordx2 v[190:191], v129, s[18:19] offset:256
	global_load_dwordx2 v[192:193], v129, s[18:19] offset:288
	s_add_u32 s18, s16, 0x48000
	s_addc_u32 s19, s17, 0
	global_load_dwordx2 v[194:195], v129, s[18:19]
	global_load_dwordx2 v[196:197], v129, s[18:19] offset:32
	global_load_dwordx2 v[198:199], v129, s[18:19] offset:256
	global_load_dwordx2 v[200:201], v129, s[18:19] offset:288
	s_add_u32 s18, s16, 0x50000
	s_addc_u32 s19, s17, 0
	global_load_dwordx2 v[202:203], v129, s[18:19]
	global_load_dwordx2 v[204:205], v129, s[18:19] offset:32
	global_load_dwordx2 v[206:207], v129, s[18:19] offset:256
	global_load_dwordx2 v[208:209], v129, s[18:19] offset:288
	s_add_u32 s18, s16, 0x58000
	s_addc_u32 s19, s17, 0
	global_load_dwordx2 v[210:211], v129, s[18:19]
	global_load_dwordx2 v[212:213], v129, s[18:19] offset:32
	global_load_dwordx2 v[214:215], v129, s[18:19] offset:256
	global_load_dwordx2 v[216:217], v129, s[18:19] offset:288
	s_waitcnt vmcnt(28)
	v_lshlrev_b32_e32 v130, 16, v136
	v_and_b32_e32 v131, 0xffff0000, v136
	v_lshlrev_b32_e32 v134, 16, v137
	v_and_b32_e32 v135, 0xffff0000, v137
	v_pk_add_f32 v[124:125], v[124:125], v[130:131]
	v_pk_add_f32 v[126:127], v[126:127], v[134:135]
	v_lshlrev_b32_e32 v130, 16, v138
	v_and_b32_e32 v131, 0xffff0000, v138
	v_lshlrev_b32_e32 v134, 16, v139
	v_and_b32_e32 v135, 0xffff0000, v139
	v_pk_add_f32 v[120:121], v[120:121], v[130:131]
	v_pk_add_f32 v[122:123], v[122:123], v[134:135]
	v_lshlrev_b32_e32 v130, 16, v140
	v_and_b32_e32 v131, 0xffff0000, v140
	v_lshlrev_b32_e32 v134, 16, v141
	v_and_b32_e32 v135, 0xffff0000, v141
	v_pk_add_f32 v[116:117], v[116:117], v[130:131]
	v_pk_add_f32 v[118:119], v[118:119], v[134:135]
	v_lshlrev_b32_e32 v130, 16, v142
	v_and_b32_e32 v131, 0xffff0000, v142
	v_lshlrev_b32_e32 v134, 16, v143
	v_and_b32_e32 v135, 0xffff0000, v143
	v_pk_add_f32 v[112:113], v[112:113], v[130:131]
	v_pk_add_f32 v[114:115], v[114:115], v[134:135]
	global_store_dwordx4 v133, v[124:127], s[6:7]
	global_store_dwordx4 v133, v[120:123], s[6:7] offset:64
	global_store_dwordx4 v133, v[116:119], s[6:7] offset:512
	global_store_dwordx4 v133, v[112:115], s[6:7] offset:576
	s_waitcnt vmcnt(28)
	v_lshlrev_b32_e32 v130, 16, v144
	v_and_b32_e32 v131, 0xffff0000, v144
	v_lshlrev_b32_e32 v134, 16, v145
	v_and_b32_e32 v135, 0xffff0000, v145
	v_pk_add_f32 v[108:109], v[108:109], v[130:131]
	v_pk_add_f32 v[110:111], v[110:111], v[134:135]
	v_lshlrev_b32_e32 v130, 16, v146
	v_and_b32_e32 v131, 0xffff0000, v146
	v_lshlrev_b32_e32 v134, 16, v147
	v_and_b32_e32 v135, 0xffff0000, v147
	v_pk_add_f32 v[104:105], v[104:105], v[130:131]
	v_pk_add_f32 v[106:107], v[106:107], v[134:135]
	v_lshlrev_b32_e32 v130, 16, v148
	v_and_b32_e32 v131, 0xffff0000, v148
	v_lshlrev_b32_e32 v134, 16, v149
	v_and_b32_e32 v135, 0xffff0000, v149
	v_pk_add_f32 v[100:101], v[100:101], v[130:131]
	v_pk_add_f32 v[102:103], v[102:103], v[134:135]
	v_lshlrev_b32_e32 v130, 16, v150
	v_and_b32_e32 v131, 0xffff0000, v150
	v_lshlrev_b32_e32 v134, 16, v151
	v_and_b32_e32 v135, 0xffff0000, v151
	v_pk_add_f32 v[92:93], v[92:93], v[130:131]
	v_pk_add_f32 v[94:95], v[94:95], v[134:135]
	s_add_u32 s36, s6, 0x10000
	s_addc_u32 s37, s7, 0
	global_store_dwordx4 v133, v[108:111], s[36:37]
	global_store_dwordx4 v133, v[104:107], s[36:37] offset:64
	global_store_dwordx4 v133, v[100:103], s[36:37] offset:512
	global_store_dwordx4 v133, v[92:95], s[36:37] offset:576
	s_waitcnt vmcnt(28)
	v_lshlrev_b32_e32 v130, 16, v152
	v_and_b32_e32 v131, 0xffff0000, v152
	v_lshlrev_b32_e32 v134, 16, v153
	v_and_b32_e32 v135, 0xffff0000, v153
	v_pk_add_f32 v[96:97], v[96:97], v[130:131]
	v_pk_add_f32 v[98:99], v[98:99], v[134:135]
	v_lshlrev_b32_e32 v130, 16, v154
	v_and_b32_e32 v131, 0xffff0000, v154
	v_lshlrev_b32_e32 v134, 16, v155
	v_and_b32_e32 v135, 0xffff0000, v155
	v_pk_add_f32 v[88:89], v[88:89], v[130:131]
	v_pk_add_f32 v[90:91], v[90:91], v[134:135]
	v_lshlrev_b32_e32 v130, 16, v156
	v_and_b32_e32 v131, 0xffff0000, v156
	v_lshlrev_b32_e32 v134, 16, v157
	v_and_b32_e32 v135, 0xffff0000, v157
	v_pk_add_f32 v[84:85], v[84:85], v[130:131]
	v_pk_add_f32 v[86:87], v[86:87], v[134:135]
	v_lshlrev_b32_e32 v130, 16, v158
	v_and_b32_e32 v131, 0xffff0000, v158
	v_lshlrev_b32_e32 v134, 16, v159
	v_and_b32_e32 v135, 0xffff0000, v159
	v_pk_add_f32 v[76:77], v[76:77], v[130:131]
	v_pk_add_f32 v[78:79], v[78:79], v[134:135]
	s_add_u32 s36, s6, 0x20000
	s_addc_u32 s37, s7, 0
	global_store_dwordx4 v133, v[96:99], s[36:37]
	global_store_dwordx4 v133, v[88:91], s[36:37] offset:64
	global_store_dwordx4 v133, v[84:87], s[36:37] offset:512
	global_store_dwordx4 v133, v[76:79], s[36:37] offset:576
	s_waitcnt vmcnt(28)
; #define PG8_BAR __builtin_amdgcn_s_barrier()
; template <class Epi, class Sched, bool ALIGN_EPI>
; DI void gemm_phase(LAS unsigned char* lds, const Gemm g, const Sched& S, const Epi& E) {
;     ...
;         if (!has_next) break;
; #pragma unroll
;         for (int a = 0; a < 2; ++a)
; #pragma unroll
;             for (int b = 0; b < 2; ++b)
; #pragma unroll
;                 for (int m = 0; m < 4; ++m)
; #pragma unroll
;                     for (int n = 0; n < 2; ++n) acc[a][b][m][n] = (f32x4){0.f, 0.f, 0.f, 0.f};
;         cur = nxt; cA = nA; cB = nB; ++ui;
;         if constexpr (ALIGN_EPI) { if (wr == 1) PG8_BAR; }
;     DI void operator()(const AccT& acc, const Unit& u, int wr, int wc, int fr, int fq, LAS unsigned char*) const {
;     ...
; #pragma unroll
;             for (int m = 0; m < 4; ++m) {
;                 const int row = u.pm * 256 + ai * 128 + wr * 64 + m * 16 + fr;
;                 float* orow = out + (size_t)row * DM + col0;
; #pragma unroll
;                 for (int bj = 0; bj < 2; ++bj)
; #pragma unroll
;                     for (int n = 0; n < 2; ++n) { const u32x2 b = xb[m][bj][n];
;                         const f32x4 xr = {__uint_as_float(b.x << 16), __uint_as_float(b.x & 0xffff0000u), __uint_as_float(b.y << 16), __uint_as_float(b.y & 0xffff0000u)};
;                         *(f32x4*)(orow + bj * 128 + n * 16) = xr + acc[ai][bj][m][n]; }
	v_lshlrev_b32_e32 v130, 16, v160
	v_and_b32_e32 v131, 0xffff0000, v160
	v_lshlrev_b32_e32 v134, 16, v161
	v_and_b32_e32 v135, 0xffff0000, v161
	v_pk_add_f32 v[80:81], v[80:81], v[130:131]
	v_pk_add_f32 v[82:83], v[82:83], v[134:135]
	v_lshlrev_b32_e32 v130, 16, v162
	v_and_b32_e32 v131, 0xffff0000, v162
	v_lshlrev_b32_e32 v134, 16, v163
	v_and_b32_e32 v135, 0xffff0000, v163
	v_pk_add_f32 v[72:73], v[72:73], v[130:131]
	v_pk_add_f32 v[74:75], v[74:75], v[134:135]
	v_lshlrev_b32_e32 v130, 16, v182
	v_and_b32_e32 v131, 0xffff0000, v182
	v_lshlrev_b32_e32 v134, 16, v183
	v_and_b32_e32 v135, 0xffff0000, v183
	v_pk_add_f32 v[68:69], v[68:69], v[130:131]
	v_pk_add_f32 v[70:71], v[70:71], v[134:135]
	v_lshlrev_b32_e32 v130, 16, v184
	v_and_b32_e32 v131, 0xffff0000, v184
	v_lshlrev_b32_e32 v134, 16, v185
	v_and_b32_e32 v135, 0xffff0000, v185
	v_pk_add_f32 v[64:65], v[64:65], v[130:131]
	v_pk_add_f32 v[66:67], v[66:67], v[134:135]
	s_add_u32 s36, s6, 0x30000
	s_addc_u32 s37, s7, 0
	global_store_dwordx4 v133, v[80:83], s[36:37]
	global_store_dwordx4 v133, v[72:75], s[36:37] offset:64
	global_store_dwordx4 v133, v[68:71], s[36:37] offset:512
	global_store_dwordx4 v133, v[64:67], s[36:37] offset:576
	s_waitcnt vmcnt(28)
	v_lshlrev_b32_e32 v130, 16, v186
	v_and_b32_e32 v131, 0xffff0000, v186
	v_lshlrev_b32_e32 v134, 16, v187
	v_and_b32_e32 v135, 0xffff0000, v187
	v_pk_add_f32 v[60:61], v[60:61], v[130:131]
	v_pk_add_f32 v[62:63], v[62:63], v[134:135]
	v_lshlrev_b32_e32 v130, 16, v188
	v_and_b32_e32 v131, 0xffff0000, v188
	v_lshlrev_b32_e32 v134, 16, v189
	v_and_b32_e32 v135, 0xffff0000, v189
	v_pk_add_f32 v[56:57], v[56:57], v[130:131]
	v_pk_add_f32 v[58:59], v[58:59], v[134:135]
	v_lshlrev_b32_e32 v130, 16, v190
	v_and_b32_e32 v131, 0xffff0000, v190
	v_lshlrev_b32_e32 v134, 16, v191
	v_and_b32_e32 v135, 0xffff0000, v191
	v_pk_add_f32 v[52:53], v[52:53], v[130:131]
	v_pk_add_f32 v[54:55], v[54:55], v[134:135]
	v_lshlrev_b32_e32 v130, 16, v192
	v_and_b32_e32 v131, 0xffff0000, v192
	v_lshlrev_b32_e32 v134, 16, v193
	v_and_b32_e32 v135, 0xffff0000, v193
	v_pk_add_f32 v[44:45], v[44:45], v[130:131]
	v_pk_add_f32 v[46:47], v[46:47], v[134:135]
	s_add_u32 s36, s6, 0x80000
	s_addc_u32 s37, s7, 0
	global_store_dwordx4 v133, v[60:63], s[36:37]
	global_store_dwordx4 v133, v[56:59], s[36:37] offset:64
	global_store_dwordx4 v133, v[52:55], s[36:37] offset:512
	global_store_dwordx4 v133, v[44:47], s[36:37] offset:576
	s_waitcnt vmcnt(28)
	v_lshlrev_b32_e32 v130, 16, v194
	v_and_b32_e32 v131, 0xffff0000, v194
	v_lshlrev_b32_e32 v134, 16, v195
	v_and_b32_e32 v135, 0xffff0000, v195
	v_pk_add_f32 v[48:49], v[48:49], v[130:131]
	v_pk_add_f32 v[50:51], v[50:51], v[134:135]
	v_lshlrev_b32_e32 v130, 16, v196
	v_and_b32_e32 v131, 0xffff0000, v196
	v_lshlrev_b32_e32 v134, 16, v197
	v_and_b32_e32 v135, 0xffff0000, v197
	v_pk_add_f32 v[40:41], v[40:41], v[130:131]
	v_pk_add_f32 v[42:43], v[42:43], v[134:135]
	v_lshlrev_b32_e32 v130, 16, v198
	v_and_b32_e32 v131, 0xffff0000, v198
	v_lshlrev_b32_e32 v134, 16, v199
	v_and_b32_e32 v135, 0xffff0000, v199
	v_pk_add_f32 v[36:37], v[36:37], v[130:131]
	v_pk_add_f32 v[38:39], v[38:39], v[134:135]
	v_lshlrev_b32_e32 v130, 16, v200
	v_and_b32_e32 v131, 0xffff0000, v200
	v_lshlrev_b32_e32 v134, 16, v201
	v_and_b32_e32 v135, 0xffff0000, v201
	v_pk_add_f32 v[28:29], v[28:29], v[130:131]
	v_pk_add_f32 v[30:31], v[30:31], v[134:135]
	s_add_u32 s36, s6, 0x90000
	s_addc_u32 s37, s7, 0
	global_store_dwordx4 v133, v[48:51], s[36:37]
	global_store_dwordx4 v133, v[40:43], s[36:37] offset:64
	global_store_dwordx4 v133, v[36:39], s[36:37] offset:512
	global_store_dwordx4 v133, v[28:31], s[36:37] offset:576
	s_waitcnt vmcnt(28)
	v_lshlrev_b32_e32 v130, 16, v202
	v_and_b32_e32 v131, 0xffff0000, v202
	v_lshlrev_b32_e32 v134, 16, v203
	v_and_b32_e32 v135, 0xffff0000, v203
	v_pk_add_f32 v[32:33], v[32:33], v[130:131]
	v_pk_add_f32 v[34:35], v[34:35], v[134:135]
	v_lshlrev_b32_e32 v130, 16, v204
	v_and_b32_e32 v131, 0xffff0000, v204
	v_lshlrev_b32_e32 v134, 16, v205
	v_and_b32_e32 v135, 0xffff0000, v205
	v_pk_add_f32 v[24:25], v[24:25], v[130:131]
	v_pk_add_f32 v[26:27], v[26:27], v[134:135]
	v_lshlrev_b32_e32 v130, 16, v206
	v_and_b32_e32 v131, 0xffff0000, v206
	v_lshlrev_b32_e32 v134, 16, v207
	v_and_b32_e32 v135, 0xffff0000, v207
	v_pk_add_f32 v[20:21], v[20:21], v[130:131]
	v_pk_add_f32 v[22:23], v[22:23], v[134:135]
	v_lshlrev_b32_e32 v130, 16, v208
	v_and_b32_e32 v131, 0xffff0000, v208
	v_lshlrev_b32_e32 v134, 16, v209
	v_and_b32_e32 v135, 0xffff0000, v209
	v_pk_add_f32 v[12:13], v[12:13], v[130:131]
	v_pk_add_f32 v[14:15], v[14:15], v[134:135]
	s_add_u32 s36, s6, 0xa0000
	s_addc_u32 s37, s7, 0
	global_store_dwordx4 v133, v[32:35], s[36:37]
	global_store_dwordx4 v133, v[24:27], s[36:37] offset:64
	global_store_dwordx4 v133, v[20:23], s[36:37] offset:512
	global_store_dwordx4 v133, v[12:15], s[36:37] offset:576
	s_waitcnt vmcnt(28)
	v_lshlrev_b32_e32 v130, 16, v210
	v_and_b32_e32 v131, 0xffff0000, v210
	v_lshlrev_b32_e32 v134, 16, v211
	v_and_b32_e32 v135, 0xffff0000, v211
	v_pk_add_f32 v[16:17], v[16:17], v[130:131]
	v_pk_add_f32 v[18:19], v[18:19], v[134:135]
	v_lshlrev_b32_e32 v130, 16, v212
	v_and_b32_e32 v131, 0xffff0000, v212
	v_lshlrev_b32_e32 v134, 16, v213
	v_and_b32_e32 v135, 0xffff0000, v213
	v_pk_add_f32 v[8:9], v[8:9], v[130:131]
	v_pk_add_f32 v[10:11], v[10:11], v[134:135]
	v_lshlrev_b32_e32 v130, 16, v214
	v_and_b32_e32 v131, 0xffff0000, v214
	v_lshlrev_b32_e32 v134, 16, v215
	v_and_b32_e32 v135, 0xffff0000, v215
	v_pk_add_f32 v[4:5], v[4:5], v[130:131]
	v_pk_add_f32 v[6:7], v[6:7], v[134:135]
	v_lshlrev_b32_e32 v130, 16, v216
	v_and_b32_e32 v131, 0xffff0000, v216
	v_lshlrev_b32_e32 v134, 16, v217
	v_and_b32_e32 v135, 0xffff0000, v217
	v_pk_add_f32 v[0:1], v[0:1], v[130:131]
	v_pk_add_f32 v[2:3], v[2:3], v[134:135]
	s_add_u32 s36, s6, 0xb0000
	s_addc_u32 s37, s7, 0
	global_store_dwordx4 v133, v[16:19], s[36:37]
	global_store_dwordx4 v133, v[8:11], s[36:37] offset:64
	global_store_dwordx4 v133, v[4:7], s[36:37] offset:512
	global_store_dwordx4 v133, v[0:3], s[36:37] offset:576
	s_mov_b64 s[0:1], -1
	s_cmp_eq_u32 s33, s29
	s_cbranch_scc1 .LBB0_787
	s_and_b64 s[0:1], s[14:15], exec
	s_cselect_b32 s30, s22, s30
	s_cselect_b32 s21, s34, s21
	s_andn2_b64 vcc, exec, s[8:9]
	s_cbranch_vccnz .LBB0_786
	s_barrier
	s_branch .LBB0_786
